# resid prompt loops: the 7 late loads of each 4-row item issued before the first wait (counted vmcnt instead of a full drain between two load groups)
# baseline (speedup 1.0000x reference)
.LBB0_716:
	s_and_b32 s68, s67, 7
	s_lshl_b32 s68, s68, 2
	s_lshr_b32 s69, s67, 6
	s_add_i32 s68, s68, s69
	s_lshl_b32 s68, s68, 3
	s_bfe_u32 s69, s67, 0x30003
	s_or_b32 s2, s68, s69
	s_and_b32 s68, s2, 7
	s_and_b32 s69, s2, -8
	s_or_b32 s2, s69, s68
	s_add_i32 s58, s2, 0x4000
	s_ashr_i32 s59, s58, 31
	v_mov_b32_e32 v133, v134
	s_lshl_b64 s[2:3], s[58:59], 9
	s_add_u32 s2, s28, s2
	v_ashrrev_i32_e32 v97, 5, v133
	s_waitcnt vmcnt(0)
	v_and_b32_e32 v83, 3, v133
	s_addc_u32 s3, s30, s3
	v_lshlrev_b32_e32 v0, 7, v83
	v_mov_b32_e32 v1, v96
	v_lshlrev_b32_e32 v2, 3, v97
	v_lshl_add_u64 v[0:1], s[2:3], 0, v[0:1]
	v_ashrrev_i32_e32 v3, 31, v2
	v_lshl_add_u64 v[0:1], v[2:3], 1, v[0:1]
	s_mul_i32 s2, s58, 0x2800
	global_load_dwordx4 v[48:51], v[0:1], off
	global_load_dwordx4 v[52:55], v[0:1], off offset:32
	global_load_dwordx4 v[56:59], v[0:1], off offset:64
	global_load_dwordx4 v[60:63], v[0:1], off offset:96
	s_mul_hi_i32 s3, s58, 0x2800
	s_add_u32 s2, s14, s2
	v_mul_u32_u24_e32 v0, 3, v83
	s_addc_u32 s3, s15, s3
	v_lshlrev_b32_e32 v0, 2, v0
	v_mov_b32_e32 v1, v96
	v_lshl_add_u64 v[0:1], s[2:3], 0, v[0:1]
	s_mov_b32 s2, 0xdea2000
	v_add_co_u32_e32 v0, vcc, s2, v0
	v_add_u32_e32 v104, s90, v133
	s_nop 0
	v_addc_co_u32_e32 v1, vcc, 0, v1, vcc
	global_load_dwordx3 v[80:82], v[0:1], off offset:2080
	v_cmp_gt_i32_e32 vcc, 64, v104
	v_lshl_add_u32 v105, v104, 2, 0
	s_waitcnt vmcnt(0)
	s_barrier
	v_cmp_nlt_f32_e64 s[54:55], s34, v80
	v_cmp_ngt_f32_e64 s[56:57], s35, v80
	v_cmp_nlt_f32_e64 s[50:51], s34, v81
	v_cmp_ngt_f32_e64 s[46:47], s35, v81
	v_cmp_nlt_f32_e64 s[52:53], s34, v82
	v_cmp_ngt_f32_e64 s[48:49], s35, v82
	s_and_saveexec_b64 s[4:5], vcc
	v_add_u32_e32 v0, 0x13000, v105
	ds_write_b32 v0, v96
	s_or_b64 exec, exec, s[4:5]
	v_mov_b32_e32 v2, v133
	v_readlane_b32 s2, v254, 40
	v_ashrrev_i32_e32 v0, 1, v2
	s_ashr_i32 s62, s58, 3
	s_addk_i32 s62, 0xf800
	v_add_u32_e32 v0, s2, v0
	s_movk_i32 s2, 0x1ff
	v_cmp_gt_i32_e32 vcc, s2, v0
	s_ashr_i32 s63, s62, 31
	s_add_u32 s6, s16, s62
	v_cndmask_b32_e32 v0, 0, v0, vcc
	s_addc_u32 s7, s17, s63
	v_ashrrev_i32_e32 v1, 31, v0
	v_mov_b32_e32 v3, 0x1ff
	s_mulk_i32 s7, 0x1ff
	v_mad_u64_u32 v[0:1], s[2:3], s6, v3, v[0:1]
	v_add_u32_e32 v1, s7, v1
	v_lshlrev_b64 v[0:1], 8, v[0:1]
	v_lshlrev_b32_e32 v2, 7, v2
	v_lshl_add_u64 v[0:1], s[22:23], 0, v[0:1]
	v_and_b32_e32 v2, 0x80, v2
	v_mov_b32_e32 v3, v96
	v_lshl_add_u64 v[16:17], v[0:1], 0, v[2:3]
	v_mov_b32_e32 v0, 0
	v_mov_b32_e32 v4, 0
	v_mov_b32_e32 v5, 0
	v_mov_b32_e32 v6, 0
	v_mov_b32_e32 v7, 0
	v_mov_b32_e32 v8, 0
	v_mov_b32_e32 v9, 0
	v_mov_b32_e32 v10, 0
	v_mov_b32_e32 v11, 0
	s_and_saveexec_b64 s[4:5], vcc
	s_cbranch_execz .LBB0_720
	global_load_dwordx4 v[4:7], v[16:17], off
	global_load_dwordx4 v[8:11], v[16:17], off offset:16
